# nt on the short-conv phase's single-use projection loads, stacked on the previous best
# baseline (speedup 1.0000x reference)
.LBB0_446:
	v_add_u32_e32 v54, s4, v88
	v_ashrrev_i32_e32 v55, 31, v54
	v_lshlrev_b64 v[62:63], 15, v[54:55]
	v_lshl_add_u64 v[62:63], v[18:19], 0, v[62:63]
	v_add_u32_e32 v56, 1, v54
	v_add_u32_e32 v58, 2, v54
	v_add_u32_e32 v60, 3, v54
	v_add_co_u32_e32 v84, vcc, s7, v62
	v_lshlrev_b64 v[54:55], 12, v[54:55]
	v_ashrrev_i32_e32 v57, 31, v56
	v_ashrrev_i32_e32 v59, 31, v58
	v_ashrrev_i32_e32 v61, 31, v60
	v_addc_co_u32_e32 v85, vcc, 0, v63, vcc
	v_lshl_add_u64 v[90:91], v[20:21], 0, v[54:55]
	v_lshlrev_b64 v[54:55], 15, v[56:57]
	v_lshlrev_b64 v[56:57], 12, v[56:57]
	v_lshlrev_b64 v[68:69], 15, v[58:59]
	v_lshlrev_b64 v[70:71], 15, v[60:61]
	global_load_dwordx4 v[64:67], v[62:63], off nt
	v_add_co_u32_e32 v62, vcc, s9, v62
	v_lshl_add_u64 v[82:83], v[20:21], 0, v[56:57]
	s_nop 0
	v_addc_co_u32_e32 v63, vcc, 0, v63, vcc
	v_lshl_add_u64 v[80:81], v[18:19], 0, v[68:69]
	v_lshl_add_u64 v[56:57], v[18:19], 0, v[70:71]
	global_load_dwordx4 v[68:71], v[84:85], off nt
	global_load_dwordx4 v[72:75], v[62:63], off nt
	global_load_dwordx4 v[76:79], v[84:85], off offset:-4096 nt
	v_lshl_add_u64 v[92:93], v[18:19], 0, v[54:55]
	v_add_co_u32_e32 v94, vcc, s7, v92
	v_lshlrev_b64 v[60:61], 12, v[60:61]
	s_nop 0
	v_addc_co_u32_e32 v95, vcc, 0, v93, vcc
	v_add_co_u32_e32 v96, vcc, s9, v92
	v_lshlrev_b64 v[58:59], 12, v[58:59]
	s_nop 0
	v_addc_co_u32_e32 v97, vcc, 0, v93, vcc
	v_add_co_u32_e32 v86, vcc, s7, v80
	v_lshl_add_u64 v[54:55], v[20:21], 0, v[60:61]
	s_nop 0
	v_addc_co_u32_e32 v87, vcc, 0, v81, vcc
	v_add_co_u32_e32 v84, vcc, s9, v80
	v_lshl_add_u64 v[58:59], v[20:21], 0, v[58:59]
	s_nop 0
	v_addc_co_u32_e32 v85, vcc, 0, v81, vcc
	v_add_co_u32_e32 v60, vcc, s7, v56
	s_add_i32 s4, s4, 4
	s_nop 0
	v_addc_co_u32_e32 v61, vcc, 0, v57, vcc
	v_add_co_u32_e32 v62, vcc, s9, v56
	s_cmp_eq_u32 s4, 16
	s_nop 0
	v_addc_co_u32_e32 v63, vcc, 0, v57, vcc
	s_waitcnt vmcnt(3)
	v_lshlrev_b32_e32 v98, 16, v64
	v_and_b32_e32 v99, 0xffff0000, v64
	v_lshlrev_b32_e32 v64, 16, v65
	v_and_b32_e32 v65, 0xffff0000, v65
	v_lshlrev_b32_e32 v100, 16, v66
	v_and_b32_e32 v101, 0xffff0000, v66
	v_lshlrev_b32_e32 v66, 16, v67
	s_waitcnt vmcnt(1)
	v_lshlrev_b32_e32 v105, 16, v72
	v_and_b32_e32 v107, 0xffff0000, v72
	v_lshlrev_b32_e32 v111, 16, v73
	v_and_b32_e32 v113, 0xffff0000, v73
	v_and_b32_e32 v67, 0xffff0000, v67
	v_lshlrev_b32_e32 v102, 16, v68
	v_and_b32_e32 v103, 0xffff0000, v68
	s_waitcnt vmcnt(0)
	v_lshlrev_b32_e32 v104, 16, v76
	v_and_b32_e32 v106, 0xffff0000, v76
	v_lshlrev_b32_e32 v108, 16, v69
	v_and_b32_e32 v109, 0xffff0000, v69
	v_lshlrev_b32_e32 v110, 16, v77
	v_and_b32_e32 v112, 0xffff0000, v77
	v_lshlrev_b32_e32 v76, 16, v70
	v_and_b32_e32 v77, 0xffff0000, v70
	v_lshlrev_b32_e32 v115, 16, v74
	v_and_b32_e32 v117, 0xffff0000, v74
	v_lshlrev_b32_e32 v70, 16, v71
	v_and_b32_e32 v71, 0xffff0000, v71
	v_lshlrev_b32_e32 v119, 16, v75
	v_and_b32_e32 v75, 0xffff0000, v75
	v_mul_f32_e32 v39, 0xbfb8aa3b, v105
	v_mul_f32_e32 v41, 0xbfb8aa3b, v107
	v_mul_f32_e32 v45, 0xbfb8aa3b, v111
	v_mul_f32_e32 v51, 0xbfb8aa3b, v113
	v_lshlrev_b32_e32 v114, 16, v78
	v_and_b32_e32 v116, 0xffff0000, v78
	v_lshlrev_b32_e32 v118, 16, v79
	v_and_b32_e32 v74, 0xffff0000, v79
	v_pk_mul_f32 v[68:69], v[98:99], v[102:103]
	v_pk_mul_f32 v[72:73], v[64:65], v[108:109]
	v_pk_mul_f32 v[76:77], v[100:101], v[76:77]
	v_mul_f32_e32 v53, 0xbfb8aa3b, v115
	v_mul_f32_e32 v64, 0xbfb8aa3b, v117
	v_pk_mul_f32 v[78:79], v[66:67], v[70:71]
	v_mul_f32_e32 v65, 0xbfb8aa3b, v119
	v_mul_f32_e32 v66, 0xbfb8aa3b, v75
	v_exp_f32_e32 v89, v39
	v_exp_f32_e32 v99, v41
	v_exp_f32_e32 v101, v45
	v_exp_f32_e32 v103, v51
	v_mov_b32_e32 v43, v68
	v_mov_b32_e32 v47, v69
	v_mov_b32_e32 v49, v73
	v_mov_b32_e32 v51, v77
	v_exp_f32_e32 v109, v53
	v_exp_f32_e32 v121, v64
	v_mov_b32_e32 v53, v79
	v_exp_f32_e32 v123, v65
	v_exp_f32_e32 v125, v66
	v_mov_b32_e32 v39, v72
	v_mov_b32_e32 v45, v76
	v_mov_b32_e32 v41, v78
	v_pk_mul_f32 v[64:65], v[22:23], v[42:43]
	v_pk_mul_f32 v[66:67], v[2:3], v[46:47]
	v_pk_mul_f32 v[128:129], v[4:5], v[48:49]
	v_pk_mul_f32 v[132:133], v[6:7], v[50:51]
	v_pk_mul_f32 v[136:137], v[8:9], v[52:53]
	v_pk_mul_f32 v[70:71], v[24:25], v[38:39]
	v_pk_mul_f32 v[130:131], v[26:27], v[44:45]
	v_pk_mul_f32 v[134:135], v[28:29], v[40:41]
	v_fma_f32 v32, v10, v32, v64
	v_fma_f32 v33, v11, v33, v66
	v_fma_f32 v31, v13, v31, v128
	v_fma_f32 v37, v15, v37, v132
	v_fma_f32 v35, v17, v35, v136
	v_fma_f32 v39, v12, v30, v70
	v_fma_f32 v41, v14, v36, v130
	v_fma_f32 v43, v16, v34, v134
	v_add_f32_e32 v30, v32, v65
	v_add_f32_e32 v32, v33, v67
	v_add_f32_e32 v36, v31, v129
	v_add_f32_e32 v66, v37, v133
	v_add_f32_e32 v128, v35, v137
	v_add_f32_e32 v31, 1.0, v89
	v_add_f32_e32 v33, 1.0, v99
	v_add_f32_e32 v35, 1.0, v101
	v_add_f32_e32 v37, 1.0, v103
	v_add_f32_e32 v34, v39, v71
	v_add_f32_e32 v64, v41, v131
	v_add_f32_e32 v70, v43, v135
	v_add_f32_e32 v39, 1.0, v109
	v_add_f32_e32 v41, 1.0, v121
	v_add_f32_e32 v43, 1.0, v123
	v_add_f32_e32 v45, 1.0, v125
	v_rcp_f32_e32 v31, v31
	v_rcp_f32_e32 v33, v33
	v_rcp_f32_e32 v35, v35
	v_rcp_f32_e32 v37, v37
	v_rcp_f32_e32 v65, v39
	v_rcp_f32_e32 v67, v41
	v_rcp_f32_e32 v71, v43
	v_rcp_f32_e32 v129, v45
	v_pk_mul_f32 v[30:31], v[30:31], v[104:105]
	v_pk_mul_f32 v[32:33], v[32:33], v[106:107]
	v_pk_mul_f32 v[34:35], v[34:35], v[110:111]
	v_pk_mul_f32 v[36:37], v[36:37], v[112:113]
	v_pk_mul_f32 v[64:65], v[64:65], v[114:115]
	v_pk_mul_f32 v[66:67], v[66:67], v[116:117]
	v_pk_mul_f32 v[70:71], v[70:71], v[118:119]
	v_pk_mul_f32 v[74:75], v[128:129], v[74:75]
	v_mul_f32_e32 v30, v30, v31
	v_mul_f32_e32 v31, v32, v33
	v_mul_f32_e32 v32, v34, v35
	v_mul_f32_e32 v33, v36, v37
	v_mul_f32_e32 v34, v64, v65
	v_mul_f32_e32 v35, v66, v67
	v_mul_f32_e32 v36, v70, v71
	v_mul_f32_e32 v37, v74, v75
	v_cvt_pk_bf16_f32 v30, v30, v31
	v_cvt_pk_bf16_f32 v31, v32, v33
	v_cvt_pk_bf16_f32 v32, v34, v35
	v_cvt_pk_bf16_f32 v33, v36, v37
	global_store_dwordx4 v[90:91], v[30:33], off
	global_load_dwordx4 v[30:33], v[92:93], off nt
	s_nop 0
	global_load_dwordx4 v[34:37], v[94:95], off nt
	global_load_dwordx4 v[64:67], v[96:97], off nt
	global_load_dwordx4 v[90:93], v[94:95], off offset:-4096 nt
	v_mov_b32_e32 v98, v68
	v_mov_b32_e32 v100, v69
	v_mov_b32_e32 v102, v72
	v_mov_b32_e32 v108, v73
	v_mov_b32_e32 v120, v76
	v_mov_b32_e32 v122, v77
	v_mov_b32_e32 v124, v78
	v_mov_b32_e32 v126, v79
	s_waitcnt vmcnt(3)
	v_lshlrev_b32_e32 v70, 16, v30
	v_and_b32_e32 v71, 0xffff0000, v30
	s_waitcnt vmcnt(2)
	v_lshlrev_b32_e32 v74, 16, v34
	v_and_b32_e32 v75, 0xffff0000, v34
	s_waitcnt vmcnt(1)
	v_lshlrev_b32_e32 v95, 16, v64
	v_and_b32_e32 v97, 0xffff0000, v64
	v_lshlrev_b32_e32 v30, 16, v31
	v_and_b32_e32 v31, 0xffff0000, v31
	v_lshlrev_b32_e32 v34, 16, v35
	v_and_b32_e32 v35, 0xffff0000, v35
	v_lshlrev_b32_e32 v105, 16, v65
	v_and_b32_e32 v107, 0xffff0000, v65
	s_waitcnt vmcnt(0)
	v_lshlrev_b32_e32 v94, 16, v90
	v_and_b32_e32 v96, 0xffff0000, v90
	v_lshlrev_b32_e32 v104, 16, v91
	v_and_b32_e32 v106, 0xffff0000, v91
	v_lshlrev_b32_e32 v90, 16, v32
	v_and_b32_e32 v91, 0xffff0000, v32
	v_lshlrev_b32_e32 v110, 16, v36
	v_and_b32_e32 v111, 0xffff0000, v36
	v_lshlrev_b32_e32 v113, 16, v66
	v_and_b32_e32 v115, 0xffff0000, v66
	v_lshlrev_b32_e32 v32, 16, v33
	v_and_b32_e32 v33, 0xffff0000, v33
	v_lshlrev_b32_e32 v36, 16, v37
	v_and_b32_e32 v37, 0xffff0000, v37
	v_lshlrev_b32_e32 v117, 16, v67
	v_and_b32_e32 v119, 0xffff0000, v67
	v_mul_f32_e32 v39, 0xbfb8aa3b, v95
	v_mul_f32_e32 v41, 0xbfb8aa3b, v97
	v_pk_mul_f32 v[66:67], v[30:31], v[34:35]
	v_mul_f32_e32 v30, 0xbfb8aa3b, v105
	v_mul_f32_e32 v31, 0xbfb8aa3b, v107
	v_pk_mul_f32 v[64:65], v[70:71], v[74:75]
	v_mul_f32_e32 v34, 0xbfb8aa3b, v113
	v_mul_f32_e32 v35, 0xbfb8aa3b, v115
	v_pk_mul_f32 v[74:75], v[32:33], v[36:37]
	v_mul_f32_e32 v32, 0xbfb8aa3b, v117
	v_mul_f32_e32 v33, 0xbfb8aa3b, v119
	v_exp_f32_e32 v39, v39
	v_exp_f32_e32 v41, v41
	v_exp_f32_e32 v43, v30
	v_exp_f32_e32 v45, v31
	v_mov_b32_e32 v99, v64
	v_mov_b32_e32 v101, v65
	v_mov_b32_e32 v103, v66
	v_mov_b32_e32 v109, v67
	v_exp_f32_e32 v47, v34
	v_exp_f32_e32 v49, v35
	v_exp_f32_e32 v51, v32
	v_exp_f32_e32 v53, v33
	v_pk_mul_f32 v[30:31], v[22:23], v[98:99]
	v_pk_mul_f32 v[32:33], v[2:3], v[100:101]
	v_pk_mul_f32 v[34:35], v[24:25], v[102:103]
	v_pk_mul_f32 v[36:37], v[4:5], v[108:109]
	v_fma_f32 v30, v10, v42, v30
	v_fma_f32 v32, v11, v46, v32
	v_fma_f32 v34, v12, v38, v34
	v_fma_f32 v36, v13, v48, v36
	v_add_f32_e32 v30, v30, v31
	v_add_f32_e32 v32, v32, v33
	v_add_f32_e32 v34, v34, v35
	v_add_f32_e32 v36, v36, v37
	v_add_f32_e32 v31, 1.0, v39
	v_add_f32_e32 v33, 1.0, v41
	v_add_f32_e32 v35, 1.0, v43
	v_add_f32_e32 v37, 1.0, v45
	v_pk_mul_f32 v[70:71], v[90:91], v[110:111]
	v_add_f32_e32 v39, 1.0, v47
	v_add_f32_e32 v41, 1.0, v49
	v_add_f32_e32 v43, 1.0, v51
	v_add_f32_e32 v45, 1.0, v53
	v_rcp_f32_e32 v31, v31
	v_rcp_f32_e32 v33, v33
	v_rcp_f32_e32 v35, v35
	v_rcp_f32_e32 v37, v37
	v_mov_b32_e32 v121, v70
	v_mov_b32_e32 v123, v71
	v_mov_b32_e32 v125, v74
	v_mov_b32_e32 v127, v75
	v_rcp_f32_e32 v39, v39
	v_rcp_f32_e32 v41, v41
	v_rcp_f32_e32 v43, v43
	v_rcp_f32_e32 v45, v45
	v_pk_mul_f32 v[98:99], v[26:27], v[120:121]
	v_pk_mul_f32 v[100:101], v[6:7], v[122:123]
	v_pk_mul_f32 v[102:103], v[28:29], v[124:125]
	v_pk_mul_f32 v[108:109], v[8:9], v[126:127]
	v_fma_f32 v38, v14, v44, v98
	v_fma_f32 v42, v15, v50, v100
	v_fma_f32 v44, v16, v40, v102
	v_fma_f32 v46, v17, v52, v108
	v_lshlrev_b32_e32 v112, 16, v92
	v_and_b32_e32 v114, 0xffff0000, v92
	v_lshlrev_b32_e32 v116, 16, v93
	v_and_b32_e32 v118, 0xffff0000, v93
	v_add_f32_e32 v38, v38, v99
	v_add_f32_e32 v40, v42, v101
	v_add_f32_e32 v42, v44, v103
	v_add_f32_e32 v44, v46, v109
	v_pk_mul_f32 v[30:31], v[30:31], v[94:95]
	v_pk_mul_f32 v[32:33], v[32:33], v[96:97]
	v_pk_mul_f32 v[34:35], v[34:35], v[104:105]
	v_pk_mul_f32 v[36:37], v[36:37], v[106:107]
	v_pk_mul_f32 v[38:39], v[38:39], v[112:113]
	v_pk_mul_f32 v[40:41], v[40:41], v[114:115]
	v_pk_mul_f32 v[42:43], v[42:43], v[116:117]
	v_pk_mul_f32 v[44:45], v[44:45], v[118:119]
	v_mul_f32_e32 v30, v30, v31
	v_mul_f32_e32 v31, v32, v33
	v_mul_f32_e32 v32, v34, v35
	v_mul_f32_e32 v33, v36, v37
	v_mul_f32_e32 v34, v38, v39
	v_mul_f32_e32 v35, v40, v41
	v_mul_f32_e32 v36, v42, v43
	v_mul_f32_e32 v37, v44, v45
	v_cvt_pk_bf16_f32 v30, v30, v31
	v_cvt_pk_bf16_f32 v31, v32, v33
	v_cvt_pk_bf16_f32 v32, v34, v35
	v_cvt_pk_bf16_f32 v33, v36, v37
	global_store_dwordx4 v[82:83], v[30:33], off
	global_load_dwordx4 v[30:33], v[80:81], off nt
	s_nop 0
	global_load_dwordx4 v[34:37], v[86:87], off nt
	global_load_dwordx4 v[38:41], v[84:85], off nt
	global_load_dwordx4 v[42:45], v[86:87], off offset:-4096 nt
	v_mov_b32_e32 v128, v67
	v_mov_b32_e32 v90, v64
	v_mov_b32_e32 v92, v65
	v_mov_b32_e32 v110, v66
	v_mov_b32_e32 v132, v71
	v_mov_b32_e32 v134, v74
	v_mov_b32_e32 v136, v75
	v_mov_b32_e32 v130, v70
	s_waitcnt vmcnt(3)
	v_lshlrev_b32_e32 v46, 16, v30
	v_and_b32_e32 v47, 0xffff0000, v30
	s_waitcnt vmcnt(2)
	v_lshlrev_b32_e32 v48, 16, v34
	v_and_b32_e32 v49, 0xffff0000, v34
	s_waitcnt vmcnt(1)
	v_lshlrev_b32_e32 v81, 16, v39
	v_and_b32_e32 v39, 0xffff0000, v39
	v_lshlrev_b32_e32 v99, 16, v41
	v_and_b32_e32 v41, 0xffff0000, v41
	v_lshlrev_b32_e32 v51, 16, v38
	s_waitcnt vmcnt(0)
	v_lshlrev_b32_e32 v50, 16, v42
	v_and_b32_e32 v53, 0xffff0000, v38
	v_and_b32_e32 v52, 0xffff0000, v42
	v_lshlrev_b32_e32 v30, 16, v31
	v_and_b32_e32 v31, 0xffff0000, v31
	v_lshlrev_b32_e32 v34, 16, v35
	v_and_b32_e32 v35, 0xffff0000, v35
	v_lshlrev_b32_e32 v80, 16, v43
	v_and_b32_e32 v38, 0xffff0000, v43
	v_lshlrev_b32_e32 v42, 16, v32
	v_and_b32_e32 v43, 0xffff0000, v32
	v_lshlrev_b32_e32 v82, 16, v36
	v_and_b32_e32 v83, 0xffff0000, v36
	v_lshlrev_b32_e32 v85, 16, v40
	v_and_b32_e32 v87, 0xffff0000, v40
	v_lshlrev_b32_e32 v94, 16, v33
	v_and_b32_e32 v95, 0xffff0000, v33
	v_lshlrev_b32_e32 v96, 16, v37
	v_and_b32_e32 v97, 0xffff0000, v37
	v_pk_mul_f32 v[32:33], v[46:47], v[48:49]
	v_mul_f32_e32 v47, 0xbfb8aa3b, v39
	v_mul_f32_e32 v49, 0xbfb8aa3b, v41
	v_lshlrev_b32_e32 v84, 16, v44
	v_and_b32_e32 v86, 0xffff0000, v44
	v_lshlrev_b32_e32 v98, 16, v45
	v_and_b32_e32 v40, 0xffff0000, v45
	v_mul_f32_e32 v44, 0xbfb8aa3b, v51
	v_mul_f32_e32 v45, 0xbfb8aa3b, v53
	v_pk_mul_f32 v[30:31], v[30:31], v[34:35]
	v_mul_f32_e32 v46, 0xbfb8aa3b, v81
	v_pk_mul_f32 v[36:37], v[42:43], v[82:83]
	v_mul_f32_e32 v42, 0xbfb8aa3b, v85
	v_mul_f32_e32 v43, 0xbfb8aa3b, v87
	v_pk_mul_f32 v[34:35], v[94:95], v[96:97]
	v_mul_f32_e32 v48, 0xbfb8aa3b, v99
	v_exp_f32_e32 v97, v47
	v_exp_f32_e32 v107, v49
	v_exp_f32_e32 v83, v44
	v_exp_f32_e32 v89, v45
	v_mov_b32_e32 v129, v31
	v_exp_f32_e32 v95, v46
	v_exp_f32_e32 v101, v42
	v_exp_f32_e32 v103, v43
	v_exp_f32_e32 v105, v48
	v_mov_b32_e32 v91, v32
	v_mov_b32_e32 v93, v33
	v_mov_b32_e32 v111, v30
	v_mov_b32_e32 v133, v37
	v_mov_b32_e32 v135, v34
	v_mov_b32_e32 v137, v35
	v_pk_mul_f32 v[48:49], v[4:5], v[128:129]
	v_mov_b32_e32 v131, v36
	v_pk_mul_f32 v[42:43], v[22:23], v[90:91]
	v_pk_mul_f32 v[44:45], v[2:3], v[92:93]
	v_pk_mul_f32 v[46:47], v[24:25], v[110:111]
	v_pk_mul_f32 v[92:93], v[6:7], v[132:133]
	v_pk_mul_f32 v[110:111], v[28:29], v[134:135]
	v_pk_mul_f32 v[112:113], v[8:9], v[136:137]
	v_fma_f32 v48, v13, v73, v48
	v_pk_mul_f32 v[90:91], v[26:27], v[130:131]
	v_fma_f32 v42, v10, v68, v42
	v_fma_f32 v44, v11, v69, v44
	v_fma_f32 v46, v12, v72, v46
	v_fma_f32 v69, v15, v77, v92
	v_fma_f32 v73, v16, v78, v110
	v_fma_f32 v77, v17, v79, v112
	v_add_f32_e32 v48, v48, v49
	v_add_f32_e32 v49, 1.0, v97
	v_add_f32_e32 v79, 1.0, v107
	v_fma_f32 v68, v14, v76, v90
	v_add_f32_e32 v42, v42, v43
	v_add_f32_e32 v44, v44, v45
	v_add_f32_e32 v46, v46, v47
	v_add_f32_e32 v72, v69, v93
	v_add_f32_e32 v76, v73, v111
	v_add_f32_e32 v78, v77, v113
	v_add_f32_e32 v43, 1.0, v83
	v_add_f32_e32 v45, 1.0, v89
	v_add_f32_e32 v47, 1.0, v95
	v_add_f32_e32 v69, 1.0, v101
	v_add_f32_e32 v73, 1.0, v103
	v_add_f32_e32 v77, 1.0, v105
	v_rcp_f32_e32 v49, v49
	v_rcp_f32_e32 v79, v79
	v_rcp_f32_e32 v43, v43
	v_rcp_f32_e32 v45, v45
	v_rcp_f32_e32 v47, v47
	v_rcp_f32_e32 v69, v69
	v_rcp_f32_e32 v73, v73
	v_rcp_f32_e32 v77, v77
	v_add_f32_e32 v68, v68, v91
	v_pk_mul_f32 v[38:39], v[48:49], v[38:39]
	v_pk_mul_f32 v[40:41], v[78:79], v[40:41]
	v_pk_mul_f32 v[42:43], v[42:43], v[50:51]
	v_pk_mul_f32 v[44:45], v[44:45], v[52:53]
	v_pk_mul_f32 v[46:47], v[46:47], v[80:81]
	v_pk_mul_f32 v[48:49], v[68:69], v[84:85]
	v_pk_mul_f32 v[50:51], v[72:73], v[86:87]
	v_pk_mul_f32 v[52:53], v[76:77], v[98:99]
	v_mul_f32_e32 v39, v38, v39
	v_mul_f32_e32 v41, v40, v41
	v_mul_f32_e32 v42, v42, v43
	v_mul_f32_e32 v43, v44, v45
	v_mul_f32_e32 v44, v46, v47
	v_mul_f32_e32 v45, v48, v49
	v_mul_f32_e32 v46, v50, v51
	v_mul_f32_e32 v47, v52, v53
	v_cvt_pk_bf16_f32 v38, v42, v43
	v_cvt_pk_bf16_f32 v39, v44, v39
	v_cvt_pk_bf16_f32 v40, v45, v46
	v_cvt_pk_bf16_f32 v41, v47, v41
	global_store_dwordx4 v[58:59], v[38:41], off
	global_load_dwordx4 v[38:41], v[56:57], off nt
	s_nop 0
	global_load_dwordx4 v[42:45], v[60:61], off nt
	global_load_dwordx4 v[46:49], v[62:63], off nt
	global_load_dwordx4 v[50:53], v[60:61], off offset:-4096 nt
	v_mov_b32_e32 v82, v32
	v_mov_b32_e32 v94, v33
	v_mov_b32_e32 v96, v30
	v_mov_b32_e32 v100, v31
	v_mov_b32_e32 v102, v36
	v_mov_b32_e32 v104, v37
	v_mov_b32_e32 v106, v34
	v_mov_b32_e32 v108, v35
	s_waitcnt vmcnt(3)
	v_lshlrev_b32_e32 v56, 16, v38
	v_and_b32_e32 v57, 0xffff0000, v38
	s_waitcnt vmcnt(1)
	v_lshlrev_b32_e32 v61, 16, v46
	s_waitcnt vmcnt(0)
	v_lshlrev_b32_e32 v60, 16, v50
	v_and_b32_e32 v63, 0xffff0000, v46
	v_and_b32_e32 v62, 0xffff0000, v50
	v_lshlrev_b32_e32 v73, 16, v47
	v_lshlrev_b32_e32 v72, 16, v51
	v_and_b32_e32 v77, 0xffff0000, v47
	v_and_b32_e32 v76, 0xffff0000, v51
	v_lshlrev_b32_e32 v46, 16, v40
	v_and_b32_e32 v47, 0xffff0000, v40
	v_lshlrev_b32_e32 v50, 16, v44
	v_and_b32_e32 v51, 0xffff0000, v44
	v_lshlrev_b32_e32 v79, 16, v48
	v_and_b32_e32 v81, 0xffff0000, v48
	v_lshlrev_b32_e32 v87, 16, v49
	v_and_b32_e32 v91, 0xffff0000, v49
	v_lshlrev_b32_e32 v58, 16, v42
	v_and_b32_e32 v59, 0xffff0000, v42
	v_lshlrev_b32_e32 v38, 16, v39
	v_and_b32_e32 v39, 0xffff0000, v39
	v_lshlrev_b32_e32 v68, 16, v43
	v_and_b32_e32 v69, 0xffff0000, v43
	v_lshlrev_b32_e32 v78, 16, v52
	v_and_b32_e32 v80, 0xffff0000, v52
	v_lshlrev_b32_e32 v84, 16, v45
	v_and_b32_e32 v85, 0xffff0000, v45
	v_lshlrev_b32_e32 v86, 16, v53
	v_and_b32_e32 v90, 0xffff0000, v53
	v_mul_f32_e32 v48, 0xbfb8aa3b, v61
	v_mul_f32_e32 v49, 0xbfb8aa3b, v63
	v_mul_f32_e32 v52, 0xbfb8aa3b, v73
	v_mul_f32_e32 v53, 0xbfb8aa3b, v77
	v_pk_mul_f32 v[44:45], v[46:47], v[50:51]
	v_mul_f32_e32 v46, 0xbfb8aa3b, v79
	v_mul_f32_e32 v47, 0xbfb8aa3b, v81
	v_mul_f32_e32 v50, 0xbfb8aa3b, v87
	v_mul_f32_e32 v51, 0xbfb8aa3b, v91
	v_lshlrev_b32_e32 v40, 16, v41
	v_and_b32_e32 v41, 0xffff0000, v41
	v_pk_mul_f32 v[42:43], v[56:57], v[58:59]
	v_pk_mul_f32 v[38:39], v[38:39], v[68:69]
	v_exp_f32_e32 v89, v48
	v_exp_f32_e32 v49, v49
	v_exp_f32_e32 v98, v52
	v_exp_f32_e32 v53, v53
	v_exp_f32_e32 v99, v46
	v_exp_f32_e32 v47, v47
	v_exp_f32_e32 v110, v50
	v_exp_f32_e32 v51, v51
	v_pk_mul_f32 v[40:41], v[40:41], v[84:85]
	v_mov_b32_e32 v83, v42
	v_mov_b32_e32 v95, v43
	v_mov_b32_e32 v97, v38
	v_mov_b32_e32 v101, v39
	v_mov_b32_e32 v103, v44
	v_mov_b32_e32 v105, v45
	v_mov_b32_e32 v107, v40
	v_mov_b32_e32 v109, v41
	v_pk_mul_f32 v[56:57], v[22:23], v[82:83]
	v_pk_mul_f32 v[58:59], v[2:3], v[94:95]
	v_pk_mul_f32 v[68:69], v[24:25], v[96:97]
	v_pk_mul_f32 v[82:83], v[4:5], v[100:101]
	v_mov_b32_e32 v46, v43
	v_mov_b32_e32 v48, v39
	v_mov_b32_e32 v50, v45
	v_mov_b32_e32 v52, v41
	v_pk_mul_f32 v[84:85], v[26:27], v[102:103]
	v_pk_mul_f32 v[92:93], v[6:7], v[104:105]
	v_pk_mul_f32 v[94:95], v[28:29], v[106:107]
	v_pk_mul_f32 v[96:97], v[8:9], v[108:109]
	v_fma_f32 v39, v10, v64, v56
	v_fma_f32 v41, v11, v65, v58
	v_fma_f32 v43, v12, v66, v68
	v_fma_f32 v45, v13, v67, v82
	v_fma_f32 v65, v14, v70, v84
	v_fma_f32 v67, v15, v71, v92
	v_fma_f32 v71, v16, v74, v94
	v_fma_f32 v75, v17, v75, v96
	v_add_f32_e32 v56, v39, v57
	v_add_f32_e32 v58, v41, v59
	v_add_f32_e32 v64, v43, v69
	v_add_f32_e32 v66, v45, v83
	v_add_f32_e32 v39, 1.0, v89
	v_add_f32_e32 v41, 1.0, v49
	v_add_f32_e32 v43, 1.0, v98
	v_add_f32_e32 v45, 1.0, v53
	v_add_f32_e32 v49, 1.0, v99
	v_add_f32_e32 v47, 1.0, v47
	v_add_f32_e32 v53, 1.0, v110
	v_add_f32_e32 v51, 1.0, v51
	v_add_f32_e32 v68, v65, v85
	v_add_f32_e32 v70, v67, v93
	v_add_f32_e32 v74, v71, v95
	v_add_f32_e32 v82, v75, v97
	v_rcp_f32_e32 v57, v39
	v_rcp_f32_e32 v59, v41
	v_rcp_f32_e32 v65, v43
	v_rcp_f32_e32 v67, v45
	v_rcp_f32_e32 v69, v49
	v_rcp_f32_e32 v71, v47
	v_rcp_f32_e32 v75, v53
	v_rcp_f32_e32 v83, v51
	v_pk_mul_f32 v[56:57], v[56:57], v[60:61]
	v_pk_mul_f32 v[58:59], v[58:59], v[62:63]
	v_pk_mul_f32 v[60:61], v[64:65], v[72:73]
	v_pk_mul_f32 v[62:63], v[66:67], v[76:77]
	v_pk_mul_f32 v[64:65], v[68:69], v[78:79]
	v_pk_mul_f32 v[66:67], v[70:71], v[80:81]
	v_pk_mul_f32 v[68:69], v[74:75], v[86:87]
	v_pk_mul_f32 v[70:71], v[82:83], v[90:91]
	v_mul_f32_e32 v39, v56, v57
	v_mul_f32_e32 v41, v58, v59
	v_mul_f32_e32 v43, v60, v61
	v_mul_f32_e32 v45, v62, v63
	v_mul_f32_e32 v47, v64, v65
	v_mul_f32_e32 v49, v66, v67
	v_mul_f32_e32 v51, v68, v69
	v_mul_f32_e32 v53, v70, v71
	v_cvt_pk_bf16_f32 v56, v39, v41
	v_cvt_pk_bf16_f32 v57, v43, v45
	v_cvt_pk_bf16_f32 v58, v47, v49
	v_cvt_pk_bf16_f32 v59, v51, v53
	global_store_dwordx4 v[54:55], v[56:59], off
	s_cbranch_scc0 .LBB0_446
	s_add_i32 s6, s6, s3
	s_cmpk_gt_i32 s6, 0x1ff
	v_add_u32_e32 v88, s8, v88
	s_cbranch_scc0 .LBB0_443

.LBB0_673:
	v_add_u32_e32 v54, s4, v88
	v_ashrrev_i32_e32 v55, 31, v54
	v_lshlrev_b64 v[62:63], 15, v[54:55]
	v_lshl_add_u64 v[62:63], v[18:19], 0, v[62:63]
	v_add_u32_e32 v56, 1, v54
	v_add_u32_e32 v58, 2, v54
	v_add_u32_e32 v60, 3, v54
	v_add_co_u32_e32 v84, vcc, s7, v62
	v_lshlrev_b64 v[54:55], 12, v[54:55]
	v_ashrrev_i32_e32 v57, 31, v56
	v_ashrrev_i32_e32 v59, 31, v58
	v_ashrrev_i32_e32 v61, 31, v60
	v_addc_co_u32_e32 v85, vcc, 0, v63, vcc
	v_lshl_add_u64 v[90:91], v[20:21], 0, v[54:55]
	v_lshlrev_b64 v[54:55], 15, v[56:57]
	v_lshlrev_b64 v[56:57], 12, v[56:57]
	v_lshlrev_b64 v[68:69], 15, v[58:59]
	v_lshlrev_b64 v[70:71], 15, v[60:61]
	global_load_dwordx4 v[64:67], v[62:63], off nt
	v_add_co_u32_e32 v62, vcc, s9, v62
	v_lshl_add_u64 v[82:83], v[20:21], 0, v[56:57]
	s_nop 0
	v_addc_co_u32_e32 v63, vcc, 0, v63, vcc
	v_lshl_add_u64 v[80:81], v[18:19], 0, v[68:69]
	v_lshl_add_u64 v[56:57], v[18:19], 0, v[70:71]
	global_load_dwordx4 v[68:71], v[84:85], off nt
	global_load_dwordx4 v[72:75], v[62:63], off nt
	global_load_dwordx4 v[76:79], v[84:85], off offset:-4096 nt
	v_lshl_add_u64 v[92:93], v[18:19], 0, v[54:55]
	v_add_co_u32_e32 v94, vcc, s7, v92
	v_lshlrev_b64 v[60:61], 12, v[60:61]
	s_nop 0
	v_addc_co_u32_e32 v95, vcc, 0, v93, vcc
	v_add_co_u32_e32 v96, vcc, s9, v92
	v_lshlrev_b64 v[58:59], 12, v[58:59]
	s_nop 0
	v_addc_co_u32_e32 v97, vcc, 0, v93, vcc
	v_add_co_u32_e32 v84, vcc, s7, v80
	v_lshl_add_u64 v[54:55], v[20:21], 0, v[60:61]
	s_nop 0
	v_addc_co_u32_e32 v85, vcc, 0, v81, vcc
	v_add_co_u32_e32 v86, vcc, s9, v80
	v_lshl_add_u64 v[58:59], v[20:21], 0, v[58:59]
	s_nop 0
	v_addc_co_u32_e32 v87, vcc, 0, v81, vcc
	v_add_co_u32_e32 v60, vcc, s7, v56
	s_add_i32 s4, s4, 4
	s_nop 0
	v_addc_co_u32_e32 v61, vcc, 0, v57, vcc
	v_add_co_u32_e32 v62, vcc, s9, v56
	s_cmp_eq_u32 s4, 16
	s_nop 0
	v_addc_co_u32_e32 v63, vcc, 0, v57, vcc
	s_waitcnt vmcnt(3)
	v_lshlrev_b32_e32 v98, 16, v64
	v_and_b32_e32 v99, 0xffff0000, v64
	v_lshlrev_b32_e32 v64, 16, v65
	v_and_b32_e32 v65, 0xffff0000, v65
	v_lshlrev_b32_e32 v100, 16, v66
	v_and_b32_e32 v101, 0xffff0000, v66
	v_lshlrev_b32_e32 v66, 16, v67
	s_waitcnt vmcnt(1)
	v_lshlrev_b32_e32 v105, 16, v72
	v_and_b32_e32 v107, 0xffff0000, v72
	v_lshlrev_b32_e32 v111, 16, v73
	v_and_b32_e32 v113, 0xffff0000, v73
	v_and_b32_e32 v67, 0xffff0000, v67
	v_lshlrev_b32_e32 v102, 16, v68
	v_and_b32_e32 v103, 0xffff0000, v68
	s_waitcnt vmcnt(0)
	v_lshlrev_b32_e32 v104, 16, v76
	v_and_b32_e32 v106, 0xffff0000, v76
	v_lshlrev_b32_e32 v108, 16, v69
	v_and_b32_e32 v109, 0xffff0000, v69
	v_lshlrev_b32_e32 v110, 16, v77
	v_and_b32_e32 v112, 0xffff0000, v77
	v_lshlrev_b32_e32 v76, 16, v70
	v_and_b32_e32 v77, 0xffff0000, v70
	v_lshlrev_b32_e32 v115, 16, v74
	v_and_b32_e32 v117, 0xffff0000, v74
	v_lshlrev_b32_e32 v70, 16, v71
	v_and_b32_e32 v71, 0xffff0000, v71
	v_lshlrev_b32_e32 v119, 16, v75
	v_and_b32_e32 v75, 0xffff0000, v75
	v_mul_f32_e32 v39, 0xbfb8aa3b, v105
	v_mul_f32_e32 v41, 0xbfb8aa3b, v107
	v_mul_f32_e32 v45, 0xbfb8aa3b, v111
	v_mul_f32_e32 v51, 0xbfb8aa3b, v113
	v_lshlrev_b32_e32 v114, 16, v78
	v_and_b32_e32 v116, 0xffff0000, v78
	v_lshlrev_b32_e32 v118, 16, v79
	v_and_b32_e32 v74, 0xffff0000, v79
	v_pk_mul_f32 v[68:69], v[98:99], v[102:103]
	v_pk_mul_f32 v[72:73], v[64:65], v[108:109]
	v_pk_mul_f32 v[76:77], v[100:101], v[76:77]
	v_mul_f32_e32 v53, 0xbfb8aa3b, v115
	v_mul_f32_e32 v64, 0xbfb8aa3b, v117
	v_pk_mul_f32 v[78:79], v[66:67], v[70:71]
	v_mul_f32_e32 v65, 0xbfb8aa3b, v119
	v_mul_f32_e32 v66, 0xbfb8aa3b, v75
	v_exp_f32_e32 v89, v39
	v_exp_f32_e32 v99, v41
	v_exp_f32_e32 v101, v45
	v_exp_f32_e32 v103, v51
	v_mov_b32_e32 v43, v68
	v_mov_b32_e32 v47, v69
	v_mov_b32_e32 v49, v73
	v_mov_b32_e32 v51, v77
	v_exp_f32_e32 v109, v53
	v_exp_f32_e32 v121, v64
	v_mov_b32_e32 v53, v79
	v_exp_f32_e32 v123, v65
	v_exp_f32_e32 v125, v66
	v_mov_b32_e32 v39, v72
	v_mov_b32_e32 v45, v76
	v_mov_b32_e32 v41, v78
	v_pk_mul_f32 v[64:65], v[22:23], v[42:43]
	v_pk_mul_f32 v[66:67], v[2:3], v[46:47]
	v_pk_mul_f32 v[128:129], v[4:5], v[48:49]
	v_pk_mul_f32 v[132:133], v[6:7], v[50:51]
	v_pk_mul_f32 v[136:137], v[8:9], v[52:53]
	v_pk_mul_f32 v[70:71], v[24:25], v[38:39]
	v_pk_mul_f32 v[130:131], v[26:27], v[44:45]
	v_pk_mul_f32 v[134:135], v[28:29], v[40:41]
	v_fma_f32 v32, v10, v32, v64
	v_fma_f32 v33, v11, v33, v66
	v_fma_f32 v31, v13, v31, v128
	v_fma_f32 v37, v15, v37, v132
	v_fma_f32 v35, v17, v35, v136
	v_fma_f32 v39, v12, v30, v70
	v_fma_f32 v41, v14, v36, v130
	v_fma_f32 v43, v16, v34, v134
	v_add_f32_e32 v30, v32, v65
	v_add_f32_e32 v32, v33, v67
	v_add_f32_e32 v36, v31, v129
	v_add_f32_e32 v66, v37, v133
	v_add_f32_e32 v128, v35, v137
	v_add_f32_e32 v31, 1.0, v89
	v_add_f32_e32 v33, 1.0, v99
	v_add_f32_e32 v35, 1.0, v101
	v_add_f32_e32 v37, 1.0, v103
	v_add_f32_e32 v34, v39, v71
	v_add_f32_e32 v64, v41, v131
	v_add_f32_e32 v70, v43, v135
	v_add_f32_e32 v39, 1.0, v109
	v_add_f32_e32 v41, 1.0, v121
	v_add_f32_e32 v43, 1.0, v123
	v_add_f32_e32 v45, 1.0, v125
	v_rcp_f32_e32 v31, v31
	v_rcp_f32_e32 v33, v33
	v_rcp_f32_e32 v35, v35
	v_rcp_f32_e32 v37, v37
	v_rcp_f32_e32 v65, v39
	v_rcp_f32_e32 v67, v41
	v_rcp_f32_e32 v71, v43
	v_rcp_f32_e32 v129, v45
	v_pk_mul_f32 v[30:31], v[30:31], v[104:105]
	v_pk_mul_f32 v[32:33], v[32:33], v[106:107]
	v_pk_mul_f32 v[34:35], v[34:35], v[110:111]
	v_pk_mul_f32 v[36:37], v[36:37], v[112:113]
	v_pk_mul_f32 v[64:65], v[64:65], v[114:115]
	v_pk_mul_f32 v[66:67], v[66:67], v[116:117]
	v_pk_mul_f32 v[70:71], v[70:71], v[118:119]
	v_pk_mul_f32 v[74:75], v[128:129], v[74:75]
	v_mul_f32_e32 v30, v30, v31
	v_mul_f32_e32 v31, v32, v33
	v_mul_f32_e32 v32, v34, v35
	v_mul_f32_e32 v33, v36, v37
	v_mul_f32_e32 v34, v64, v65
	v_mul_f32_e32 v35, v66, v67
	v_mul_f32_e32 v36, v70, v71
	v_mul_f32_e32 v37, v74, v75
	v_cvt_pk_bf16_f32 v30, v30, v31
	v_cvt_pk_bf16_f32 v31, v32, v33
	v_cvt_pk_bf16_f32 v32, v34, v35
	v_cvt_pk_bf16_f32 v33, v36, v37
	global_store_dwordx4 v[90:91], v[30:33], off
	global_load_dwordx4 v[30:33], v[92:93], off nt
	s_nop 0
	global_load_dwordx4 v[34:37], v[94:95], off nt
	global_load_dwordx4 v[64:67], v[96:97], off nt
	global_load_dwordx4 v[90:93], v[94:95], off offset:-4096 nt
	v_mov_b32_e32 v98, v68
	v_mov_b32_e32 v100, v69
	v_mov_b32_e32 v102, v72
	v_mov_b32_e32 v108, v73
	v_mov_b32_e32 v120, v76
	v_mov_b32_e32 v122, v77
	v_mov_b32_e32 v124, v78
	v_mov_b32_e32 v126, v79
	s_waitcnt vmcnt(3)
	v_lshlrev_b32_e32 v70, 16, v30
	v_and_b32_e32 v71, 0xffff0000, v30
	s_waitcnt vmcnt(2)
	v_lshlrev_b32_e32 v74, 16, v34
	v_and_b32_e32 v75, 0xffff0000, v34
	s_waitcnt vmcnt(1)
	v_lshlrev_b32_e32 v95, 16, v64
	v_and_b32_e32 v97, 0xffff0000, v64
	v_lshlrev_b32_e32 v30, 16, v31
	v_and_b32_e32 v31, 0xffff0000, v31
	v_lshlrev_b32_e32 v34, 16, v35
	v_and_b32_e32 v35, 0xffff0000, v35
	v_lshlrev_b32_e32 v105, 16, v65
	v_and_b32_e32 v107, 0xffff0000, v65
	s_waitcnt vmcnt(0)
	v_lshlrev_b32_e32 v94, 16, v90
	v_and_b32_e32 v96, 0xffff0000, v90
	v_lshlrev_b32_e32 v104, 16, v91
	v_and_b32_e32 v106, 0xffff0000, v91
	v_lshlrev_b32_e32 v90, 16, v32
	v_and_b32_e32 v91, 0xffff0000, v32
	v_lshlrev_b32_e32 v110, 16, v36
	v_and_b32_e32 v111, 0xffff0000, v36
	v_lshlrev_b32_e32 v113, 16, v66
	v_and_b32_e32 v115, 0xffff0000, v66
	v_lshlrev_b32_e32 v32, 16, v33
	v_and_b32_e32 v33, 0xffff0000, v33
	v_lshlrev_b32_e32 v36, 16, v37
	v_and_b32_e32 v37, 0xffff0000, v37
	v_lshlrev_b32_e32 v117, 16, v67
	v_and_b32_e32 v119, 0xffff0000, v67
	v_mul_f32_e32 v39, 0xbfb8aa3b, v95
	v_mul_f32_e32 v41, 0xbfb8aa3b, v97
	v_pk_mul_f32 v[66:67], v[30:31], v[34:35]
	v_mul_f32_e32 v30, 0xbfb8aa3b, v105
	v_mul_f32_e32 v31, 0xbfb8aa3b, v107
	v_pk_mul_f32 v[64:65], v[70:71], v[74:75]
	v_mul_f32_e32 v34, 0xbfb8aa3b, v113
	v_mul_f32_e32 v35, 0xbfb8aa3b, v115
	v_pk_mul_f32 v[74:75], v[32:33], v[36:37]
	v_mul_f32_e32 v32, 0xbfb8aa3b, v117
	v_mul_f32_e32 v33, 0xbfb8aa3b, v119
	v_exp_f32_e32 v39, v39
	v_exp_f32_e32 v41, v41
	v_exp_f32_e32 v43, v30
	v_exp_f32_e32 v45, v31
	v_mov_b32_e32 v99, v64
	v_mov_b32_e32 v101, v65
	v_mov_b32_e32 v103, v66
	v_mov_b32_e32 v109, v67
	v_exp_f32_e32 v47, v34
	v_exp_f32_e32 v49, v35
	v_exp_f32_e32 v51, v32
	v_exp_f32_e32 v53, v33
	v_pk_mul_f32 v[30:31], v[22:23], v[98:99]
	v_pk_mul_f32 v[32:33], v[2:3], v[100:101]
	v_pk_mul_f32 v[34:35], v[24:25], v[102:103]
	v_pk_mul_f32 v[36:37], v[4:5], v[108:109]
	v_fma_f32 v30, v10, v42, v30
	v_fma_f32 v32, v11, v46, v32
	v_fma_f32 v34, v12, v38, v34
	v_fma_f32 v36, v13, v48, v36
	v_add_f32_e32 v30, v30, v31
	v_add_f32_e32 v32, v32, v33
	v_add_f32_e32 v34, v34, v35
	v_add_f32_e32 v36, v36, v37
	v_add_f32_e32 v31, 1.0, v39
	v_add_f32_e32 v33, 1.0, v41
	v_add_f32_e32 v35, 1.0, v43
	v_add_f32_e32 v37, 1.0, v45
	v_pk_mul_f32 v[70:71], v[90:91], v[110:111]
	v_add_f32_e32 v39, 1.0, v47
	v_add_f32_e32 v41, 1.0, v49
	v_add_f32_e32 v43, 1.0, v51
	v_add_f32_e32 v45, 1.0, v53
	v_rcp_f32_e32 v31, v31
	v_rcp_f32_e32 v33, v33
	v_rcp_f32_e32 v35, v35
	v_rcp_f32_e32 v37, v37
	v_mov_b32_e32 v121, v70
	v_mov_b32_e32 v123, v71
	v_mov_b32_e32 v125, v74
	v_mov_b32_e32 v127, v75
	v_rcp_f32_e32 v39, v39
	v_rcp_f32_e32 v41, v41
	v_rcp_f32_e32 v43, v43
	v_rcp_f32_e32 v45, v45
	v_pk_mul_f32 v[98:99], v[26:27], v[120:121]
	v_pk_mul_f32 v[100:101], v[6:7], v[122:123]
	v_pk_mul_f32 v[102:103], v[28:29], v[124:125]
	v_pk_mul_f32 v[108:109], v[8:9], v[126:127]
	v_fma_f32 v38, v14, v44, v98
	v_fma_f32 v42, v15, v50, v100
	v_fma_f32 v44, v16, v40, v102
	v_fma_f32 v46, v17, v52, v108
	v_lshlrev_b32_e32 v112, 16, v92
	v_and_b32_e32 v114, 0xffff0000, v92
	v_lshlrev_b32_e32 v116, 16, v93
	v_and_b32_e32 v118, 0xffff0000, v93
	v_add_f32_e32 v38, v38, v99
	v_add_f32_e32 v40, v42, v101
	v_add_f32_e32 v42, v44, v103
	v_add_f32_e32 v44, v46, v109
	v_pk_mul_f32 v[30:31], v[30:31], v[94:95]
	v_pk_mul_f32 v[32:33], v[32:33], v[96:97]
	v_pk_mul_f32 v[34:35], v[34:35], v[104:105]
	v_pk_mul_f32 v[36:37], v[36:37], v[106:107]
	v_pk_mul_f32 v[38:39], v[38:39], v[112:113]
	v_pk_mul_f32 v[40:41], v[40:41], v[114:115]
	v_pk_mul_f32 v[42:43], v[42:43], v[116:117]
	v_pk_mul_f32 v[44:45], v[44:45], v[118:119]
	v_mul_f32_e32 v30, v30, v31
	v_mul_f32_e32 v31, v32, v33
	v_mul_f32_e32 v32, v34, v35
	v_mul_f32_e32 v33, v36, v37
	v_mul_f32_e32 v34, v38, v39
	v_mul_f32_e32 v35, v40, v41
	v_mul_f32_e32 v36, v42, v43
	v_mul_f32_e32 v37, v44, v45
	v_cvt_pk_bf16_f32 v30, v30, v31
	v_cvt_pk_bf16_f32 v31, v32, v33
	v_cvt_pk_bf16_f32 v32, v34, v35
	v_cvt_pk_bf16_f32 v33, v36, v37
	global_store_dwordx4 v[82:83], v[30:33], off
	global_load_dwordx4 v[30:33], v[80:81], off nt
	s_nop 0
	global_load_dwordx4 v[34:37], v[84:85], off nt
	global_load_dwordx4 v[38:41], v[86:87], off nt
	global_load_dwordx4 v[42:45], v[84:85], off offset:-4096 nt
	v_mov_b32_e32 v128, v67
	v_mov_b32_e32 v90, v64
	v_mov_b32_e32 v92, v65
	v_mov_b32_e32 v110, v66
	v_mov_b32_e32 v132, v71
	v_mov_b32_e32 v134, v74
	v_mov_b32_e32 v136, v75
	v_mov_b32_e32 v130, v70
	s_waitcnt vmcnt(3)
	v_lshlrev_b32_e32 v46, 16, v30
	v_and_b32_e32 v47, 0xffff0000, v30
	s_waitcnt vmcnt(2)
	v_lshlrev_b32_e32 v48, 16, v34
	v_and_b32_e32 v49, 0xffff0000, v34
	s_waitcnt vmcnt(1)
	v_lshlrev_b32_e32 v81, 16, v39
	v_and_b32_e32 v39, 0xffff0000, v39
	v_lshlrev_b32_e32 v99, 16, v41
	v_and_b32_e32 v41, 0xffff0000, v41
	v_lshlrev_b32_e32 v51, 16, v38
	s_waitcnt vmcnt(0)
	v_lshlrev_b32_e32 v50, 16, v42
	v_and_b32_e32 v53, 0xffff0000, v38
	v_and_b32_e32 v52, 0xffff0000, v42
	v_lshlrev_b32_e32 v30, 16, v31
	v_and_b32_e32 v31, 0xffff0000, v31
	v_lshlrev_b32_e32 v34, 16, v35
	v_and_b32_e32 v35, 0xffff0000, v35
	v_lshlrev_b32_e32 v80, 16, v43
	v_and_b32_e32 v38, 0xffff0000, v43
	v_lshlrev_b32_e32 v42, 16, v32
	v_and_b32_e32 v43, 0xffff0000, v32
	v_lshlrev_b32_e32 v82, 16, v36
	v_and_b32_e32 v83, 0xffff0000, v36
	v_lshlrev_b32_e32 v85, 16, v40
	v_and_b32_e32 v87, 0xffff0000, v40
	v_lshlrev_b32_e32 v94, 16, v33
	v_and_b32_e32 v95, 0xffff0000, v33
	v_lshlrev_b32_e32 v96, 16, v37
	v_and_b32_e32 v97, 0xffff0000, v37
	v_pk_mul_f32 v[32:33], v[46:47], v[48:49]
	v_mul_f32_e32 v47, 0xbfb8aa3b, v39
	v_mul_f32_e32 v49, 0xbfb8aa3b, v41
	v_lshlrev_b32_e32 v84, 16, v44
	v_and_b32_e32 v86, 0xffff0000, v44
	v_lshlrev_b32_e32 v98, 16, v45
	v_and_b32_e32 v40, 0xffff0000, v45
	v_mul_f32_e32 v44, 0xbfb8aa3b, v51
	v_mul_f32_e32 v45, 0xbfb8aa3b, v53
	v_pk_mul_f32 v[30:31], v[30:31], v[34:35]
	v_mul_f32_e32 v46, 0xbfb8aa3b, v81
	v_pk_mul_f32 v[36:37], v[42:43], v[82:83]
	v_mul_f32_e32 v42, 0xbfb8aa3b, v85
	v_mul_f32_e32 v43, 0xbfb8aa3b, v87
	v_pk_mul_f32 v[34:35], v[94:95], v[96:97]
	v_mul_f32_e32 v48, 0xbfb8aa3b, v99
	v_exp_f32_e32 v97, v47
	v_exp_f32_e32 v107, v49
	v_exp_f32_e32 v83, v44
	v_exp_f32_e32 v89, v45
	v_mov_b32_e32 v129, v31
	v_exp_f32_e32 v95, v46
	v_exp_f32_e32 v101, v42
	v_exp_f32_e32 v103, v43
	v_exp_f32_e32 v105, v48
	v_mov_b32_e32 v91, v32
	v_mov_b32_e32 v93, v33
	v_mov_b32_e32 v111, v30
	v_mov_b32_e32 v133, v37
	v_mov_b32_e32 v135, v34
	v_mov_b32_e32 v137, v35
	v_pk_mul_f32 v[48:49], v[4:5], v[128:129]
	v_mov_b32_e32 v131, v36
	v_pk_mul_f32 v[42:43], v[22:23], v[90:91]
	v_pk_mul_f32 v[44:45], v[2:3], v[92:93]
	v_pk_mul_f32 v[46:47], v[24:25], v[110:111]
	v_pk_mul_f32 v[92:93], v[6:7], v[132:133]
	v_pk_mul_f32 v[110:111], v[28:29], v[134:135]
	v_pk_mul_f32 v[112:113], v[8:9], v[136:137]
	v_fma_f32 v48, v13, v73, v48
	v_pk_mul_f32 v[90:91], v[26:27], v[130:131]
	v_fma_f32 v42, v10, v68, v42
	v_fma_f32 v44, v11, v69, v44
	v_fma_f32 v46, v12, v72, v46
	v_fma_f32 v69, v15, v77, v92
	v_fma_f32 v73, v16, v78, v110
	v_fma_f32 v77, v17, v79, v112
	v_add_f32_e32 v48, v48, v49
	v_add_f32_e32 v49, 1.0, v97
	v_add_f32_e32 v79, 1.0, v107
	v_fma_f32 v68, v14, v76, v90
	v_add_f32_e32 v42, v42, v43
	v_add_f32_e32 v44, v44, v45
	v_add_f32_e32 v46, v46, v47
	v_add_f32_e32 v72, v69, v93
	v_add_f32_e32 v76, v73, v111
	v_add_f32_e32 v78, v77, v113
	v_add_f32_e32 v43, 1.0, v83
	v_add_f32_e32 v45, 1.0, v89
	v_add_f32_e32 v47, 1.0, v95
	v_add_f32_e32 v69, 1.0, v101
	v_add_f32_e32 v73, 1.0, v103
	v_add_f32_e32 v77, 1.0, v105
	v_rcp_f32_e32 v49, v49
	v_rcp_f32_e32 v79, v79
	v_rcp_f32_e32 v43, v43
	v_rcp_f32_e32 v45, v45
	v_rcp_f32_e32 v47, v47
	v_rcp_f32_e32 v69, v69
	v_rcp_f32_e32 v73, v73
	v_rcp_f32_e32 v77, v77
	v_add_f32_e32 v68, v68, v91
	v_pk_mul_f32 v[38:39], v[48:49], v[38:39]
	v_pk_mul_f32 v[40:41], v[78:79], v[40:41]
	v_pk_mul_f32 v[42:43], v[42:43], v[50:51]
	v_pk_mul_f32 v[44:45], v[44:45], v[52:53]
	v_pk_mul_f32 v[46:47], v[46:47], v[80:81]
	v_pk_mul_f32 v[48:49], v[68:69], v[84:85]
	v_pk_mul_f32 v[50:51], v[72:73], v[86:87]
	v_pk_mul_f32 v[52:53], v[76:77], v[98:99]
	v_mul_f32_e32 v39, v38, v39
	v_mul_f32_e32 v41, v40, v41
	v_mul_f32_e32 v42, v42, v43
	v_mul_f32_e32 v43, v44, v45
	v_mul_f32_e32 v44, v46, v47
	v_mul_f32_e32 v45, v48, v49
	v_mul_f32_e32 v46, v50, v51
	v_mul_f32_e32 v47, v52, v53
	v_cvt_pk_bf16_f32 v38, v42, v43
	v_cvt_pk_bf16_f32 v39, v44, v39
	v_cvt_pk_bf16_f32 v40, v45, v46
	v_cvt_pk_bf16_f32 v41, v47, v41
	global_store_dwordx4 v[58:59], v[38:41], off
	global_load_dwordx4 v[38:41], v[56:57], off nt
	s_nop 0
	global_load_dwordx4 v[42:45], v[60:61], off nt
	global_load_dwordx4 v[46:49], v[62:63], off nt
	global_load_dwordx4 v[50:53], v[60:61], off offset:-4096 nt
	v_mov_b32_e32 v82, v32
	v_mov_b32_e32 v94, v33
	v_mov_b32_e32 v96, v30
	v_mov_b32_e32 v100, v31
	v_mov_b32_e32 v102, v36
	v_mov_b32_e32 v104, v37
	v_mov_b32_e32 v106, v34
	v_mov_b32_e32 v108, v35
	s_waitcnt vmcnt(3)
	v_lshlrev_b32_e32 v56, 16, v38
	v_and_b32_e32 v57, 0xffff0000, v38
	s_waitcnt vmcnt(1)
	v_lshlrev_b32_e32 v61, 16, v46
	s_waitcnt vmcnt(0)
	v_lshlrev_b32_e32 v60, 16, v50
	v_and_b32_e32 v63, 0xffff0000, v46
	v_and_b32_e32 v62, 0xffff0000, v50
	v_lshlrev_b32_e32 v73, 16, v47
	v_lshlrev_b32_e32 v72, 16, v51
	v_and_b32_e32 v77, 0xffff0000, v47
	v_and_b32_e32 v76, 0xffff0000, v51
	v_lshlrev_b32_e32 v46, 16, v40
	v_and_b32_e32 v47, 0xffff0000, v40
	v_lshlrev_b32_e32 v50, 16, v44
	v_and_b32_e32 v51, 0xffff0000, v44
	v_lshlrev_b32_e32 v79, 16, v48
	v_and_b32_e32 v81, 0xffff0000, v48
	v_lshlrev_b32_e32 v87, 16, v49
	v_and_b32_e32 v91, 0xffff0000, v49
	v_lshlrev_b32_e32 v58, 16, v42
	v_and_b32_e32 v59, 0xffff0000, v42
	v_lshlrev_b32_e32 v38, 16, v39
	v_and_b32_e32 v39, 0xffff0000, v39
	v_lshlrev_b32_e32 v68, 16, v43
	v_and_b32_e32 v69, 0xffff0000, v43
	v_lshlrev_b32_e32 v78, 16, v52
	v_and_b32_e32 v80, 0xffff0000, v52
	v_lshlrev_b32_e32 v84, 16, v45
	v_and_b32_e32 v85, 0xffff0000, v45
	v_lshlrev_b32_e32 v86, 16, v53
	v_and_b32_e32 v90, 0xffff0000, v53
	v_mul_f32_e32 v48, 0xbfb8aa3b, v61
	v_mul_f32_e32 v49, 0xbfb8aa3b, v63
	v_mul_f32_e32 v52, 0xbfb8aa3b, v73
	v_mul_f32_e32 v53, 0xbfb8aa3b, v77
	v_pk_mul_f32 v[44:45], v[46:47], v[50:51]
	v_mul_f32_e32 v46, 0xbfb8aa3b, v79
	v_mul_f32_e32 v47, 0xbfb8aa3b, v81
	v_mul_f32_e32 v50, 0xbfb8aa3b, v87
	v_mul_f32_e32 v51, 0xbfb8aa3b, v91
	v_lshlrev_b32_e32 v40, 16, v41
	v_and_b32_e32 v41, 0xffff0000, v41
	v_pk_mul_f32 v[42:43], v[56:57], v[58:59]
	v_pk_mul_f32 v[38:39], v[38:39], v[68:69]
	v_exp_f32_e32 v89, v48
	v_exp_f32_e32 v49, v49
	v_exp_f32_e32 v98, v52
	v_exp_f32_e32 v53, v53
	v_exp_f32_e32 v99, v46
	v_exp_f32_e32 v47, v47
	v_exp_f32_e32 v110, v50
	v_exp_f32_e32 v51, v51
	v_pk_mul_f32 v[40:41], v[40:41], v[84:85]
	v_mov_b32_e32 v83, v42
	v_mov_b32_e32 v95, v43
	v_mov_b32_e32 v97, v38
	v_mov_b32_e32 v101, v39
	v_mov_b32_e32 v103, v44
	v_mov_b32_e32 v105, v45
	v_mov_b32_e32 v107, v40
	v_mov_b32_e32 v109, v41
	v_pk_mul_f32 v[56:57], v[22:23], v[82:83]
	v_pk_mul_f32 v[58:59], v[2:3], v[94:95]
	v_pk_mul_f32 v[68:69], v[24:25], v[96:97]
	v_pk_mul_f32 v[82:83], v[4:5], v[100:101]
	v_mov_b32_e32 v46, v43
	v_mov_b32_e32 v48, v39
	v_mov_b32_e32 v50, v45
	v_mov_b32_e32 v52, v41
	v_pk_mul_f32 v[84:85], v[26:27], v[102:103]
	v_pk_mul_f32 v[92:93], v[6:7], v[104:105]
	v_pk_mul_f32 v[94:95], v[28:29], v[106:107]
	v_pk_mul_f32 v[96:97], v[8:9], v[108:109]
	v_fma_f32 v39, v10, v64, v56
	v_fma_f32 v41, v11, v65, v58
	v_fma_f32 v43, v12, v66, v68
	v_fma_f32 v45, v13, v67, v82
	v_fma_f32 v65, v14, v70, v84
	v_fma_f32 v67, v15, v71, v92
	v_fma_f32 v71, v16, v74, v94
	v_fma_f32 v75, v17, v75, v96
	v_add_f32_e32 v56, v39, v57
	v_add_f32_e32 v58, v41, v59
	v_add_f32_e32 v64, v43, v69
	v_add_f32_e32 v66, v45, v83
	v_add_f32_e32 v39, 1.0, v89
	v_add_f32_e32 v41, 1.0, v49
	v_add_f32_e32 v43, 1.0, v98
	v_add_f32_e32 v45, 1.0, v53
	v_add_f32_e32 v49, 1.0, v99
	v_add_f32_e32 v47, 1.0, v47
	v_add_f32_e32 v53, 1.0, v110
	v_add_f32_e32 v51, 1.0, v51
	v_add_f32_e32 v68, v65, v85
	v_add_f32_e32 v70, v67, v93
	v_add_f32_e32 v74, v71, v95
	v_add_f32_e32 v82, v75, v97
	v_rcp_f32_e32 v57, v39
	v_rcp_f32_e32 v59, v41
	v_rcp_f32_e32 v65, v43
	v_rcp_f32_e32 v67, v45
	v_rcp_f32_e32 v69, v49
	v_rcp_f32_e32 v71, v47
	v_rcp_f32_e32 v75, v53
	v_rcp_f32_e32 v83, v51
	v_pk_mul_f32 v[56:57], v[56:57], v[60:61]
	v_pk_mul_f32 v[58:59], v[58:59], v[62:63]
	v_pk_mul_f32 v[60:61], v[64:65], v[72:73]
	v_pk_mul_f32 v[62:63], v[66:67], v[76:77]
	v_pk_mul_f32 v[64:65], v[68:69], v[78:79]
	v_pk_mul_f32 v[66:67], v[70:71], v[80:81]
	v_pk_mul_f32 v[68:69], v[74:75], v[86:87]
	v_pk_mul_f32 v[70:71], v[82:83], v[90:91]
	v_mul_f32_e32 v39, v56, v57
	v_mul_f32_e32 v41, v58, v59
	v_mul_f32_e32 v43, v60, v61
	v_mul_f32_e32 v45, v62, v63
	v_mul_f32_e32 v47, v64, v65
	v_mul_f32_e32 v49, v66, v67
	v_mul_f32_e32 v51, v68, v69
	v_mul_f32_e32 v53, v70, v71
	v_cvt_pk_bf16_f32 v56, v39, v41
	v_cvt_pk_bf16_f32 v57, v43, v45
	v_cvt_pk_bf16_f32 v58, v47, v49
	v_cvt_pk_bf16_f32 v59, v51, v53
	global_store_dwordx4 v[54:55], v[56:59], off
	s_cbranch_scc0 .LBB0_673
	s_add_i32 s6, s6, s3
	s_cmpk_gt_i32 s6, 0x1ff
	v_add_u32_e32 v88, s8, v88
	s_cbranch_scc0 .LBB0_670
